# v29 + fox copy-1 q loads issued together with the cumsum loads (one shared wait)
# baseline (speedup 1.0000x reference)
; DI float ex2(float x) { return __builtin_amdgcn_exp2f(x); }
; DI void fox_unit(const bf16* PR, const float* AUX, const float* bfp, bf16* MIX, char* sm, int b, int h, int qb, bool do_cs) {
;     ...
;     if (do_cs) {
;         float v[4]; float run = 0.f; const float bias = bfp[h];
; #pragma unroll
;         for (int e = 0; e < 4; ++e) { const int s = 4 * tid + e; float ls = 0.f;
;             if (s < nkeys) { const float x = AUX[(rb + s) * 32 + h] + bias; ls = fminf(x, 0.f) - 0.6931471805599453f * __builtin_amdgcn_logf(1.f + ex2(-1.4426950408889634f * fabsf(x))); }
;             run += ls; v[e] = run; }
;         float tot = run;
; #pragma unroll
;         for (int o = 1; o < 64; o <<= 1) { const float y = __shfl_up(tot, o); if (lane >= o) tot += y; }
;         if (lane == 63) miscf[24 + wid] = tot;
;         __syncthreads();
;         float off = tot - run;
;         for (int w = 0; w < wid; ++w) off += miscf[24 + w];
; #pragma unroll
;         for (int e = 0; e < 4; ++e) cbuf[4 * tid + e] = v[e] + off;
;         __syncthreads();
;     }
;     const int t = q0 + 32 * wid + r32;
;     bf16x8 qr[5];
; #pragma unroll
;     for (int d0 = 0; d0 < 4; ++d0) qr[d0] = *(const bf16x8*)(PR + (rb + t) * NP + C_FQ + 64 * h + 16 * d0 + 8 * hi);
.LBB0_291:
	s_and_b32 s12, s25, 3
	s_lshr_b32 s3, s25, 2
	s_mul_i32 s2, s3, 0x2aab
	s_lshr_b32 s4, s2, 31
	s_lshr_b32 s2, s2, 16
	s_add_i32 s2, s2, s4
	s_sub_i32 s13, 7, s12
	s_mul_i32 s4, s2, 6
	s_lshl_b32 s26, s13, 8
	s_sub_i32 s8, s3, s4
	s_add_i32 s9, s26, 0x100
	s_bfe_i64 s[4:5], s[2:3], 0x100000
	s_bfe_i64 s[2:3], s[8:9], 0x100000
	s_lshl_b64 s[14:15], s[4:5], 11
	s_lshl_b64 s[2:3], s[2:3], 2
	s_add_u32 s6, s1, s2
	v_mov_b32_e32 v170, v172
	s_addc_u32 s7, s24, s3
	global_load_dword v0, v1, s[6:7]
	v_readlane_b32 s6, v245, 46
	v_lshlrev_b32_e32 v4, 2, v170
	v_readlane_b32 s7, v245, 47
	s_add_u32 s2, s6, s2
	v_readfirstlane_b32 s18, v170
	s_addc_u32 s3, s7, s3
	v_ashrrev_i32_e32 v5, 31, v4
	v_lshl_add_u64 v[6:7], s[14:15], 0, v[4:5]
	v_lshlrev_b64 v[6:7], 7, v[6:7]
	v_lshl_add_u64 v[6:7], s[2:3], 0, v[6:7]
	global_load_dword v2, v[6:7], off
	global_load_dword v3, v[6:7], off offset:128
	global_load_dword v248, v[6:7], off offset:256
	global_load_dword v249, v[6:7], off offset:384
	s_ashr_i32 s101, s18, 6
	s_lshl_b32 s101, s101, 5
	s_add_i32 s101, s101, s26
	v_and_b32_e32 v250, 31, v170
	v_or_b32_e32 v250, s101, v250
	v_mov_b32_e32 v251, 0
	v_lshl_add_u64 v[250:251], s[14:15], 0, v[250:251]
	v_lshlrev_b64 v[250:251], 13, v[250:251]
	v_lshl_add_u64 v[250:251], s[86:87], 0, v[250:251]
	s_sext_i32_i16 s100, s8
	s_lshl_b32 s100, s100, 7
	s_ashr_i32 s101, s100, 31
	v_lshl_add_u64 v[250:251], v[250:251], 0, s[100:101]
	v_bfe_u32 v254, v170, 5, 1
	v_lshlrev_b32_e32 v254, 4, v254
	v_mov_b32_e32 v255, 0
	v_lshl_add_u64 v[250:251], v[250:251], 0, v[254:255]
	global_load_dwordx4 v[66:69], v[250:251], off
	global_load_dwordx4 v[70:73], v[250:251], off offset:32
	global_load_dwordx4 v[74:77], v[250:251], off offset:64
	global_load_dwordx4 v[78:81], v[250:251], off offset:96
	s_mov_b32 s10, 0xbfb8aa3b
	s_waitcnt vmcnt(0)
	v_add_f32_e32 v2, v0, v2
	v_add_f32_e32 v3, v0, v3
	v_add_f32_e32 v248, v0, v248
	v_add_f32_e32 v249, v0, v249
	v_mul_f32_e64 v5, |v2|, s10
	v_mul_f32_e64 v6, |v3|, s10
	v_mul_f32_e64 v7, |v248|, s10
	v_mul_f32_e64 v250, |v249|, s10
	v_exp_f32_e32 v5, v5
	v_exp_f32_e32 v6, v6
	v_exp_f32_e32 v7, v7
	v_exp_f32_e32 v250, v250
	v_min_f32_e32 v2, 0, v2
	v_min_f32_e32 v3, 0, v3
	v_min_f32_e32 v248, 0, v248
	v_min_f32_e32 v249, 0, v249
	v_add_f32_e32 v5, 1.0, v5
	v_add_f32_e32 v6, 1.0, v6
	v_add_f32_e32 v7, 1.0, v7
	v_add_f32_e32 v250, 1.0, v250
	v_log_f32_e32 v5, v5
	v_log_f32_e32 v6, v6
	v_log_f32_e32 v7, v7
	v_log_f32_e32 v250, v250
	s_nop 0
	v_fmac_f32_e32 v2, 0xbf317218, v5
	v_fmac_f32_e32 v3, 0xbf317218, v6
	v_fmac_f32_e32 v248, 0xbf317218, v7
	v_fmac_f32_e32 v249, 0xbf317218, v250
	v_add_f32_e32 v2, 0, v2
	v_cmp_gt_i32_e32 vcc, s9, v4
	v_or_b32_e32 v6, 1, v4
	s_nop 0
	v_cndmask_b32_e32 v2, 0, v2, vcc
	v_cmp_gt_i32_e32 vcc, s9, v6
	v_or_b32_e32 v6, 2, v4
	s_nop 0
	v_cndmask_b32_e32 v3, 0, v3, vcc
	v_cmp_gt_i32_e32 vcc, s9, v6
	v_or_b32_e32 v6, 3, v4
	s_nop 0
	v_cndmask_b32_e32 v7, 0, v248, vcc
	v_cmp_gt_i32_e32 vcc, s9, v6
	s_nop 1
	v_cndmask_b32_e32 v5, 0, v249, vcc
	v_and_b32_e32 v8, 64, v181
	s_waitcnt vmcnt(0)
	v_add_u32_e32 v0, -1, v181
	v_add_f32_e32 v3, v2, v3
	v_cmp_lt_i32_e32 vcc, v0, v8
	v_add_f32_e32 v4, v3, v7
	v_add_f32_e32 v5, v4, v5
	v_cndmask_b32_e32 v0, v0, v181, vcc
	v_lshlrev_b32_e32 v0, 2, v0
	ds_bpermute_b32 v0, v0, v5
	v_add_u32_e32 v6, -2, v181
	v_and_b32_e32 v171, 63, v170
	v_cmp_lt_i32_e32 vcc, v6, v8
	v_cmp_eq_u32_e64 s[2:3], 0, v171
	s_waitcnt lgkmcnt(0)
	v_add_f32_e32 v0, v5, v0
	v_cndmask_b32_e32 v6, v6, v181, vcc
	v_cndmask_b32_e64 v0, v0, v5, s[2:3]
	v_lshlrev_b32_e32 v6, 2, v6
	ds_bpermute_b32 v6, v6, v0
	v_cmp_gt_u32_e32 vcc, 2, v171
	s_ashr_i32 s27, s18, 6
	s_waitcnt lgkmcnt(0)
	v_add_f32_e32 v6, v0, v6
	v_cndmask_b32_e32 v0, v6, v0, vcc
	v_add_u32_e32 v6, -4, v181
	v_cmp_lt_i32_e32 vcc, v6, v8
	s_nop 1
	v_cndmask_b32_e32 v6, v6, v181, vcc
	v_lshlrev_b32_e32 v6, 2, v6
	ds_bpermute_b32 v6, v6, v0
	v_cmp_gt_u32_e32 vcc, 4, v171
	s_waitcnt lgkmcnt(0)
	v_add_f32_e32 v6, v0, v6
	v_cndmask_b32_e32 v0, v6, v0, vcc
	v_add_u32_e32 v6, -8, v181
	v_cmp_lt_i32_e32 vcc, v6, v8
	s_nop 1
	v_cndmask_b32_e32 v6, v6, v181, vcc
	v_lshlrev_b32_e32 v6, 2, v6
	ds_bpermute_b32 v6, v6, v0
	v_cmp_gt_u32_e32 vcc, 8, v171
	s_waitcnt lgkmcnt(0)
	v_add_f32_e32 v6, v0, v6
	v_cndmask_b32_e32 v0, v6, v0, vcc
	v_add_u32_e32 v6, -16, v181
	v_cmp_lt_i32_e32 vcc, v6, v8
	s_nop 1
	v_cndmask_b32_e32 v6, v6, v181, vcc
	v_lshlrev_b32_e32 v6, 2, v6
	ds_bpermute_b32 v6, v6, v0
	v_cmp_gt_u32_e32 vcc, 16, v171
	s_waitcnt lgkmcnt(0)
	v_add_f32_e32 v6, v0, v6
	v_cndmask_b32_e32 v0, v6, v0, vcc
	v_subrev_u32_e32 v6, 32, v181
	v_cmp_lt_i32_e32 vcc, v6, v8
	s_nop 1
	v_cndmask_b32_e32 v6, v6, v181, vcc
	v_lshlrev_b32_e32 v6, 2, v6
	ds_bpermute_b32 v6, v6, v0
	v_cmp_eq_u32_e32 vcc, 63, v171
	s_waitcnt lgkmcnt(0)
	v_add_f32_e32 v6, v0, v6
	s_and_saveexec_b64 s[6:7], vcc
	s_lshl_b32 s9, s27, 2
	s_add_i32 s9, s9, 0
	s_add_i32 s9, s9, 0x13560
	v_mov_b32_e32 v7, s9
	ds_write_b32 v7, v6
	s_or_b64 exec, exec, s[6:7]
	v_cmp_gt_u32_e64 s[6:7], 32, v171
	s_cmp_lt_i32 s27, 1
	s_waitcnt lgkmcnt(0)
	v_cndmask_b32_e64 v0, v6, v0, s[6:7]
	v_sub_f32_e32 v0, v0, v5
	s_barrier
	s_cbranch_scc1 .LBB0_304
	s_add_i32 s9, 0, 0x13560
	s_mov_b32 s16, s27

; #define LAS __attribute__((address_space(3)))
; DI float bf2f(unsigned h) { return __uint_as_float(h << 16); }
; DI void fox_unit(const bf16* PR, const float* AUX, const float* bfp, bf16* MIX, char* sm, int b, int h, int qb, bool do_cs) {
;     ...
;     const int t = q0 + 32 * wid + r32;
;     bf16x8 qr[5];
; #pragma unroll
;     for (int d0 = 0; d0 < 4; ++d0) qr[d0] = *(const bf16x8*)(PR + (rb + t) * NP + C_FQ + 64 * h + 16 * d0 + 8 * hi);
;     { const short one = hi ? (short)0 : (short)0x3F80; qr[4] = (bf16x8){one, one, one, 0, 0, 0, 0, 0}; }
;     const float cref = cbuf[q0];
;     const bf16* Kb = PR + rb * NP + C_FK + 64 * h; const bf16* Vb = PR + rb * NP + C_FV + 64 * h;
;     float m = MINIT, l = 0.f; f32x16 o0, o1;
; #pragma unroll
;     for (int i = 0; i < 16; ++i) { o0[i] = 0.f; o1[i] = 0.f; }
;     unsigned z_ = 0u; asm volatile("" : "+v"(z_)); u32x4 kr, vr, ar = {z_, z_, z_, z_};
;     const int wq0 = q0 + 32 * wid;
;     u32x4 zpre[4];
;     const bf16* zrow0 = PR + (rb + wq0) * NP + C_FZ + 64 * h;
;     float q1 = 0.f;
; #pragma unroll
;     for (int d0 = 0; d0 < 4; ++d0)
; #pragma unroll
;         for (int j = 0; j < 8; ++j) q1 += fabsf(bf2f((unsigned)(unsigned short)qr[d0][j]));
;     q1 += __shfl_xor(q1, 32);
;     volatile LAS unsigned* kmx = (volatile LAS unsigned*)(sm + L_MISC) + 32;
;     for (int it_ = -1, nt_ = (4 * qb + 4); it_ < nt_; ++it_) {
;         const bool more_ = it_ + 1 < nt_;
;         if (!more_) {
; #pragma unroll
;             for (int j = 0; j < 4; ++j) zpre[j] = *(const u32x4*)(zrow0 + (size_t)((lane >> 3) + 8 * j) * NP + 8 * (lane & 7));
;         }
;         if (more_) { const int kt = nt_ - 2 - it_; { kv_issue(Kb + (size_t)(64 * kt) * NP, Vb + (size_t)(64 * kt) * NP, NP, wid, lane, kr, vr);
;           if (wid == 0) ar = split3(8.f * (cref - cbuf[64 * kt + lane])); } }
.LBB0_304:
	v_lshlrev_b32_e32 v194, 4, v170
	s_lshl_b32 s20, s27, 5
	v_and_b32_e32 v6, 31, v170
	v_add_u32_e32 v7, 0, v194
	v_pk_add_f32 v[2:3], v[2:3], v[0:1] op_sel_hi:[1,0]
	v_pk_add_f32 v[4:5], v[4:5], v[0:1] op_sel_hi:[1,0]
	s_add_i32 s28, s20, s26
	ds_write_b128 v7, v[2:5] offset:36864
	v_or_b32_e32 v2, s28, v6
	s_sext_i32_i16 s8, s8
	v_ashrrev_i32_e32 v3, 31, v2
	v_lshl_add_u64 v[2:3], s[14:15], 0, v[2:3]
	s_lshl_b32 s8, s8, 6
	v_lshlrev_b64 v[2:3], 13, v[2:3]
	s_ashr_i32 s9, s8, 31
	v_lshrrev_b32_e32 v193, 5, v171
	v_lshl_add_u64 v[2:3], s[86:87], 0, v[2:3]
	s_lshl_b64 s[8:9], s[8:9], 1
	v_lshl_add_u64 v[2:3], v[2:3], 0, s[8:9]
	v_lshlrev_b32_e32 v0, 4, v193
	v_lshl_add_u64 v[2:3], v[2:3], 0, v[0:1]
	s_waitcnt lgkmcnt(0)
	s_barrier
	s_lshl_b32 s16, s26, 2
	s_add_i32 s16, s16, 0
	v_mov_b32_e32 v0, s16
	ds_read_b32 v195, v0 offset:36864
	s_lshl_b64 s[4:5], s[4:5], 24
	s_add_u32 s4, s86, s4
	s_addc_u32 s5, s87, s5
	s_add_u32 s16, s4, s8
	s_addc_u32 s17, s5, s9
	s_lshl_b32 s4, s27, 3
	s_ashr_i32 s5, s4, 31
	v_mov_b32_e32 v82, v1
	v_lshl_add_u32 v5, v171, 2, 0
	v_mov_b32_e32 v251, 0
	v_bfe_u32 v250, v171, 2, 3
	v_lshl_add_u32 v250, s27, 3, v250
	v_lshrrev_b32_e32 v246, 5, v171
	v_and_b32_e32 v247, 3, v171
	v_lshl_or_b32 v246, v246, 2, v247
	v_lshlrev_b32_e32 v247, 4, v250
	v_lshlrev_b32_e32 v250, 13, v250
	v_lshl_add_u32 v250, v246, 4, v250
	v_lshl_add_u32 v246, v246, 10, v247
	v_lshl_add_u64 v[146:147], s[16:17], 0, v[250:251]
	s_lshl_b32 s5, s27, 4
	v_lshrrev_b32_e32 v250, 2, v171
	v_and_or_b32 v250, s5, 48, v250
	s_andn2_b32 s4, s4, 31
	v_lshlrev_b32_e32 v250, 13, v250
	s_ashr_i32 s5, s4, 31
	v_lshl_add_u64 v[248:249], s[16:17], 0, v[250:251]
	s_cmp_lt_u32 s18, 64
	v_lshl_add_u64 v[248:249], s[4:5], 1, v[248:249]
	v_lshlrev_b32_e32 v250, 3, v171
	s_cselect_b64 s[18:19], -1, 0
	s_or_b32 s4, s26, 0xc0
	v_and_b32_e32 v196, 24, v250
	s_ashr_i32 s5, s4, 31
	v_lshlrev_b32_e32 v250, 1, v196
	s_lshl_b64 s[4:5], s[4:5], 13
	v_lshl_add_u64 v[158:159], v[248:249], 0, v[250:251]
	v_lshl_add_u64 v[248:249], v[146:147], 0, s[4:5]
	global_load_dwordx4 v[90:93], v[248:249], off offset:768
	v_lshl_add_u64 v[248:249], v[158:159], 0, s[4:5]
	global_load_dwordx4 v[94:97], v[248:249], off offset:1536
	s_waitcnt vmcnt(5)
	v_lshlrev_b32_e32 v0, 16, v66
	v_and_b32_e32 v2, 0xffff0000, v66
	v_add_f32_e64 v0, |v0|, |v2|
	v_lshlrev_b32_e32 v2, 16, v67
	v_add_f32_e64 v0, |v2|, v0
	v_and_b32_e32 v2, 0xffff0000, v67
	v_add_f32_e64 v0, |v2|, v0
	v_lshlrev_b32_e32 v2, 16, v68
	v_add_f32_e64 v0, |v2|, v0
	v_and_b32_e32 v2, 0xffff0000, v68
	v_add_f32_e64 v0, |v2|, v0
	v_lshlrev_b32_e32 v2, 16, v69
	v_add_f32_e64 v0, |v2|, v0
	v_and_b32_e32 v2, 0xffff0000, v69
	v_add_f32_e64 v0, |v2|, v0
	s_waitcnt vmcnt(4)
	v_lshlrev_b32_e32 v2, 16, v70
	v_add_f32_e64 v0, |v2|, v0
	v_and_b32_e32 v2, 0xffff0000, v70
	v_add_f32_e64 v0, |v2|, v0
	v_lshlrev_b32_e32 v2, 16, v71
	v_add_f32_e64 v0, |v2|, v0
	v_and_b32_e32 v2, 0xffff0000, v71
	v_add_f32_e64 v0, |v2|, v0
	v_lshlrev_b32_e32 v2, 16, v72
	v_add_f32_e64 v0, |v2|, v0
	v_and_b32_e32 v2, 0xffff0000, v72
	v_add_f32_e64 v0, |v2|, v0
	v_lshlrev_b32_e32 v2, 16, v73
	v_add_f32_e64 v0, |v2|, v0
	v_and_b32_e32 v2, 0xffff0000, v73
	v_add_f32_e64 v0, |v2|, v0
	s_waitcnt vmcnt(3)
	v_lshlrev_b32_e32 v2, 16, v74
	v_add_f32_e64 v0, |v2|, v0
	v_and_b32_e32 v2, 0xffff0000, v74
	v_add_f32_e64 v0, |v2|, v0
	v_lshlrev_b32_e32 v2, 16, v75
	v_add_f32_e64 v0, |v2|, v0
	v_and_b32_e32 v2, 0xffff0000, v75
	v_add_f32_e64 v0, |v2|, v0
	v_lshlrev_b32_e32 v2, 16, v76
	v_add_f32_e64 v0, |v2|, v0
	v_and_b32_e32 v2, 0xffff0000, v76
	v_add_f32_e64 v0, |v2|, v0
	v_lshlrev_b32_e32 v2, 16, v77
	v_add_f32_e64 v0, |v2|, v0
	v_and_b32_e32 v2, 0xffff0000, v77
	v_add_f32_e64 v0, |v2|, v0
	s_waitcnt vmcnt(2)
	v_lshlrev_b32_e32 v2, 16, v78
	v_add_f32_e64 v0, |v2|, v0
	v_and_b32_e32 v2, 0xffff0000, v78
	v_add_f32_e64 v0, |v2|, v0
	v_lshlrev_b32_e32 v2, 16, v79
	v_add_f32_e64 v0, |v2|, v0
	v_and_b32_e32 v2, 0xffff0000, v79
	v_add_f32_e64 v0, |v2|, v0
	v_lshlrev_b32_e32 v2, 16, v80
	v_add_f32_e64 v0, |v2|, v0
	v_and_b32_e32 v2, 0xffff0000, v80
	v_add_f32_e64 v0, |v2|, v0
	v_lshlrev_b32_e32 v2, 16, v81
	v_add_f32_e64 v0, |v2|, v0
	v_and_b32_e32 v2, 0xffff0000, v81
	v_add_f32_e64 v3, |v2|, v0
	v_xor_b32_e32 v0, 32, v181
	v_add_u32_e32 v2, 64, v8
	v_cmp_lt_i32_e32 vcc, v0, v2
	s_nop 1
	v_cndmask_b32_e32 v0, v181, v0, vcc
	v_lshlrev_b32_e32 v187, 2, v0
	ds_bpermute_b32 v4, v187, v3
	s_and_b64 vcc, exec, s[18:19]
	s_cbranch_vccz .LBB0_336
	v_lshl_add_u32 v0, s26, 2, v5
	ds_read_b32 v0, v0 offset:37632
	v_mov_b32_e32 v84, 0
	s_waitcnt lgkmcnt(0)
	v_sub_f32_e32 v0, v195, v0
	v_mul_f32_e32 v8, 0x41000000, v0
	v_bfe_u32 v9, v8, 16, 1
	v_add3_u32 v8, v8, v9, s93
	v_and_b32_e32 v9, 0xffff0000, v8
	v_fma_f32 v0, v0, s59, -v9
	v_bfe_u32 v9, v0, 16, 1
	v_add3_u32 v9, v0, v9, s93
	v_and_b32_e32 v9, 0xffff0000, v9
	v_sub_f32_e32 v0, v0, v9
	v_or_b32_sdwa v82, v9, v8 dst_sel:DWORD dst_unused:UNUSED_PAD src0_sel:DWORD src1_sel:WORD_1
	v_bfe_u32 v8, v0, 16, 1
	v_add3_u32 v0, v0, v8, s93
	v_lshrrev_b32_e32 v83, 16, v0
	s_branch .LBB0_337

; __global__ void __launch_bounds__(512, 2) mega_fwd(Params p) {
;     extern __shared__ __attribute__((aligned(16))) unsigned char smem[];
;     cg::grid_group grid = cg::this_grid();
;     char* sm = (char*)smem;
;     int tid_ = threadIdx.x; asm volatile("" : "+v"(tid_)); const int tid = tid_, lane = tid & 63, wid = __builtin_amdgcn_readfirstlane(tid >> 6);
	.amdhsa_kernel _Z8mega_fwd6Params
		.amdhsa_group_segment_fixed_size 0
		.amdhsa_private_segment_fixed_size 0
		.amdhsa_kernarg_size 368
		.amdhsa_user_sgpr_count 2
		.amdhsa_user_sgpr_dispatch_ptr 0
		.amdhsa_user_sgpr_queue_ptr 0
		.amdhsa_user_sgpr_kernarg_segment_ptr 1
		.amdhsa_user_sgpr_dispatch_id 0
		.amdhsa_user_sgpr_kernarg_preload_length 0
		.amdhsa_user_sgpr_kernarg_preload_offset 0
		.amdhsa_user_sgpr_private_segment_size 0
		.amdhsa_uses_dynamic_stack 0
		.amdhsa_enable_private_segment 0
		.amdhsa_system_sgpr_workgroup_id_x 1
		.amdhsa_system_sgpr_workgroup_id_y 0
		.amdhsa_system_sgpr_workgroup_id_z 0
		.amdhsa_system_sgpr_workgroup_info 0
		.amdhsa_system_vgpr_workitem_id 2
		.amdhsa_next_free_vgpr 256
		.amdhsa_next_free_sgpr 102
		.amdhsa_accum_offset 256
		.amdhsa_reserve_vcc 1
		.amdhsa_float_round_mode_32 0
		.amdhsa_float_round_mode_16_64 0
		.amdhsa_float_denorm_mode_32 3
		.amdhsa_float_denorm_mode_16_64 3
		.amdhsa_dx10_clamp 1
		.amdhsa_ieee_mode 1
		.amdhsa_fp16_overflow 0
		.amdhsa_tg_split 0
		.amdhsa_exception_fp_ieee_invalid_op 0
		.amdhsa_exception_fp_denorm_src 0
		.amdhsa_exception_fp_ieee_div_zero 0
		.amdhsa_exception_fp_ieee_overflow 0
		.amdhsa_exception_fp_ieee_underflow 0
		.amdhsa_exception_fp_ieee_inexact 0
		.amdhsa_exception_int_div_zero 0
	.end_amdhsa_kernel
